# m3: output-gate (BOG) and norm-weight loads issued with the hoisted chunk-prologue loads, so the rmsnorm tail no longer waits on them
# baseline (speedup 1.0000x reference)
.LBB0_449:
	s_ashr_i32 s2, s39, 10
	s_and_b32 s41, s39, 0x7f
	s_ashr_i32 s3, s2, 31
	v_mov_b32_e32 v23, v194
	s_lshl_b64 s[34:35], s[2:3], 13
	s_lshl_b32 s2, s41, 6
	s_bfe_u32 s42, s39, 0x30007
	v_readfirstlane_b32 s40, v23
	s_or_b32 s34, s34, s2
	v_lshrrev_b32_e32 v209, 3, v23
	v_and_b32_e32 v210, 7, v23
	v_lshlrev_b32_e32 v211, 4, v210
	v_lshl_or_b32 v190, v209, 15, v211
	v_lshlrev_b32_e32 v191, 4, v23
	v_lshl_or_b32 v192, v209, 11, v211
	v_add_u32_e32 v193, 0x1000, v192
	v_lshlrev_b32_e32 v208, 5, v210
	s_lshl_b32 s90, s42, 7
	s_or_b32 s90, s90, 0x400
	s_lshl_b64 s[52:53], s[34:35], 1
	s_add_u32 s52, s33, s52
	s_addc_u32 s53, s36, s53
	s_lshl_b32 s91, s90, 15
	s_add_u32 s52, s52, s91
	s_addc_u32 s53, s53, 0
	s_add_u32 s54, s52, 0x200000
	s_addc_u32 s55, s53, 0
	global_load_dwordx4 v[44:47], v190, s[52:53]
	global_load_dwordx4 v[48:51], v190, s[54:55]
	s_mul_i32 s92, s39, 0x4080
	s_mul_hi_i32 s93, s39, 0x4080
	s_add_u32 s92, s37, s92
	s_addc_u32 s93, s38, s93
	global_load_dwordx4 v[52:55], v191, s[92:93]
	s_add_u32 s94, s92, 0x2000
	s_addc_u32 s95, s93, 0
	global_load_dwordx4 v[56:59], v191, s[94:95]
	s_add_u32 s94, s92, 0x4000
	s_addc_u32 s95, s93, 0
	v_cmp_gt_u32_e32 vcc, 8, v23
	s_and_saveexec_b64 s[96:97], vcc
	global_load_dwordx4 v[60:63], v191, s[94:95]
	s_mov_b64 exec, s[96:97]
	s_lshl_b32 s91, s42, 8
	s_add_u32 s94, s18, s91
	s_addc_u32 s95, s19, 0
	global_load_dwordx4 v[64:67], v208, s[94:95]
	global_load_dwordx4 v[68:71], v208, s[94:95] offset:16
	global_load_dwordx4 v[72:75], v208, s[94:95] offset:2048
	global_load_dwordx4 v[76:79], v208, s[94:95] offset:2064
	s_add_u32 s94, s16, s91
	s_addc_u32 s95, s17, 0
	global_load_dwordx4 v[84:87], v208, s[94:95]
	global_load_dwordx4 v[88:91], v208, s[94:95] offset:16
	global_load_dwordx4 v[132:135], v208, s[94:95] offset:2048
	global_load_dwordx4 v[136:139], v208, s[94:95] offset:2064
	s_add_u32 s94, s94, 0x1000
	s_addc_u32 s95, s95, 0
	global_load_dwordx4 v[96:99], v208, s[94:95]
	global_load_dwordx4 v[100:103], v208, s[94:95] offset:16
	global_load_dwordx4 v[144:147], v208, s[94:95] offset:2048
	global_load_dwordx4 v[148:151], v208, s[94:95] offset:2064
	s_add_u32 s94, s94, 0x1000
	s_addc_u32 s95, s95, 0
	global_load_dwordx4 v[108:111], v208, s[94:95]
	global_load_dwordx4 v[112:115], v208, s[94:95] offset:16
	global_load_dwordx4 v[156:159], v208, s[94:95] offset:2048
	global_load_dwordx4 v[160:163], v208, s[94:95] offset:2064
	s_add_u32 s94, s94, 0x1000
	s_addc_u32 s95, s95, 0
	global_load_dwordx4 v[120:123], v208, s[94:95]
	global_load_dwordx4 v[124:127], v208, s[94:95] offset:16
	global_load_dwordx4 v[182:185], v208, s[94:95] offset:2048
	global_load_dwordx4 v[186:189], v208, s[94:95] offset:2064
	s_sub_u32 s92, s34, 3
	s_subb_u32 s93, s35, 0
	s_lshl_b64 s[92:93], s[92:93], 11
	s_add_u32 s92, s14, s92
	s_addc_u32 s93, s15, s93
	s_lshl_b32 s91, s42, 7
	s_add_u32 s92, s92, s91
	s_addc_u32 s93, s93, 0
	s_cmp_lg_u32 s41, 0
	s_cselect_b64 s[54:55], -1, 0
	v_cmp_lt_u32_e32 vcc, 2, v209
	s_or_b64 s[46:47], s[54:55], vcc
	v_cmp_lt_u32_e32 vcc, 1, v209
	s_or_b64 s[48:49], s[54:55], vcc
	v_cmp_lt_u32_e32 vcc, 0, v209
	s_or_b64 s[50:51], s[54:55], vcc
	s_mov_b64 s[96:97], exec
	s_and_b64 exec, s[96:97], s[46:47]
	global_load_dwordx4 v[80:83], v192, s[92:93]
	global_load_dwordx4 v[128:131], v192, s[92:93] offset:1024
	s_and_b64 exec, s[96:97], s[48:49]
	global_load_dwordx4 v[92:95], v192, s[92:93] offset:2048
	global_load_dwordx4 v[140:143], v192, s[92:93] offset:3072
	s_and_b64 exec, s[96:97], s[50:51]
	global_load_dwordx4 v[104:107], v193, s[92:93]
	global_load_dwordx4 v[152:155], v193, s[92:93] offset:1024
	s_mov_b64 exec, s[96:97]
	global_load_dwordx4 v[116:119], v193, s[92:93] offset:2048
	global_load_dwordx4 v[178:181], v193, s[92:93] offset:3072
	s_lshr_b32 s90, s40, 6
	s_lshl_b32 s90, s90, 3
	s_add_u32 s90, s34, s90
	s_addc_u32 s91, s35, 0
	s_lshl_b64 s[90:91], s[90:91], 11
	s_add_u32 s90, s22, s90
	s_addc_u32 s91, s23, s91
	s_lshl_b32 s92, s42, 8
	v_and_b32_e32 v232, 63, v23
	v_lshlrev_b32_e32 v233, 3, v232
	v_lshl_or_b32 v232, v232, 2, s92
	global_load_dword v224, v232, s[90:91]
	global_load_dword v225, v232, s[90:91] offset:2048
	s_add_u32 s90, s90, 0x1000
	s_addc_u32 s91, s91, 0
	global_load_dword v226, v232, s[90:91]
	global_load_dword v227, v232, s[90:91] offset:2048
	s_add_u32 s90, s90, 0x1000
	s_addc_u32 s91, s91, 0
	global_load_dword v228, v232, s[90:91]
	global_load_dword v229, v232, s[90:91] offset:2048
	s_add_u32 s90, s90, 0x1000
	s_addc_u32 s91, s91, 0
	global_load_dword v230, v232, s[90:91]
	global_load_dword v231, v232, s[90:91] offset:2048
	global_load_dwordx2 v[234:235], v233, s[20:21]
	s_cmp_gt_u32 s40, 63
	v_and_b32_e32 v22, 63, v23
	s_cbranch_scc1 .LBB0_451
	v_or_b32_e32 v0, s34, v22
	v_mov_b32_e32 v1, s35
	v_lshlrev_b64 v[0:1], 6, v[0:1]
	v_lshl_add_u64 v[0:1], s[30:31], 0, v[0:1]
	s_lshl_b32 s86, s42, 2
	v_lshl_add_u64 v[0:1], v[0:1], 0, s[86:87]
	v_mov_b32_e32 v3, s86
	global_load_dword v2, v[0:1], off offset:32
	global_load_dword v4, v3, s[26:27]
	s_nop 0
	global_load_dword v0, v[0:1], off
	s_nop 0
	global_load_dword v1, v3, s[28:29]
	s_lshl_b32 s98, s39, 4
	s_add_u32 s98, s0, s98
	s_addc_u32 s99, s1, 0
	v_mov_b32_e32 v41, 0x18100000
	global_load_dword v42, v41, s[98:99] offset:8
	s_mov_b32 s2, 0x3f317218
	s_waitcnt vmcnt(2)
	v_add_f32_e32 v2, v2, v4
	s_waitcnt vmcnt(0)
	v_add_f32_e32 v1, v0, v1
	v_min_f32_e32 v0, 0, v2
	v_mul_f32_e64 v2, |v2|, s79
	v_exp_f32_e32 v4, v2
	s_nop 0
	v_add_f32_e32 v5, 1.0, v4
	v_add_f32_e32 v2, -1.0, v5
	v_sub_f32_e32 v3, v2, v5
	v_add_f32_e32 v3, 1.0, v3
	v_sub_f32_e32 v2, v4, v2
	v_add_f32_e32 v6, v2, v3
	v_frexp_mant_f32_e32 v2, v5
	v_cmp_gt_f32_e32 vcc, s85, v2
	v_cvt_f64_f32_e32 v[2:3], v5
	v_frexp_exp_i32_f64_e32 v2, v[2:3]
	v_subbrev_co_u32_e32 v2, vcc, 0, v2, vcc
	v_sub_u32_e32 v3, 0, v2
	v_ldexp_f32 v5, v5, v3
	v_ldexp_f32 v3, v6, v3
	v_add_f32_e32 v6, -1.0, v5
	v_add_f32_e32 v7, 1.0, v6
	v_sub_f32_e32 v7, v5, v7
	v_add_f32_e32 v7, v3, v7
	v_add_f32_e32 v8, v6, v7
	v_sub_f32_e32 v6, v8, v6
	v_sub_f32_e32 v6, v7, v6
	v_add_f32_e32 v7, 1.0, v5
	v_add_f32_e32 v9, -1.0, v7
	v_sub_f32_e32 v5, v5, v9
	v_add_f32_e32 v3, v3, v5
	v_add_f32_e32 v5, v7, v3
	v_sub_f32_e32 v7, v5, v7
	v_sub_f32_e32 v3, v3, v7
	v_rcp_f32_e32 v7, v5
	v_cvt_f32_i32_e32 v2, v2
	v_mul_f32_e32 v9, v8, v7
	v_mul_f32_e32 v10, v5, v9
	v_fma_f32 v11, v9, v5, -v10
	v_fmac_f32_e32 v11, v9, v3
	v_add_f32_e32 v12, v10, v11
	v_sub_f32_e32 v13, v8, v12
	v_sub_f32_e32 v8, v8, v13
	v_sub_f32_e32 v10, v12, v10
	v_sub_f32_e32 v8, v8, v12
	v_add_f32_e32 v6, v6, v8
	v_sub_f32_e32 v8, v10, v11
	v_add_f32_e32 v6, v8, v6
	v_add_f32_e32 v8, v13, v6
	v_mul_f32_e32 v10, v7, v8
	v_mul_f32_e32 v11, v5, v10
	v_fma_f32 v5, v10, v5, -v11
	v_fmac_f32_e32 v5, v10, v3
	v_sub_f32_e32 v3, v13, v8
	v_add_f32_e32 v3, v6, v3
	v_add_f32_e32 v6, v11, v5
	v_sub_f32_e32 v12, v8, v6
	v_sub_f32_e32 v8, v8, v12
	v_sub_f32_e32 v11, v6, v11
	v_sub_f32_e32 v6, v8, v6
	v_add_f32_e32 v3, v3, v6
	v_sub_f32_e32 v5, v11, v5
	v_add_f32_e32 v3, v5, v3
	v_add_f32_e32 v5, v9, v10
	v_add_f32_e32 v3, v12, v3
	v_sub_f32_e32 v6, v5, v9
	v_mul_f32_e32 v3, v7, v3
	v_sub_f32_e32 v6, v10, v6
	v_add_f32_e32 v3, v6, v3
	v_mul_f32_e32 v9, 0x3f317218, v2
	v_add_f32_e32 v6, v5, v3
	v_fma_f32 v10, v2, s2, -v9
	v_mul_f32_e32 v7, v6, v6
	v_fmac_f32_e32 v10, 0xb102e308, v2
	v_sub_f32_e32 v2, v6, v5
	v_fmamk_f32 v8, v7, 0x3e9b6dac, v200
	v_sub_f32_e32 v2, v3, v2
	v_add_f32_e32 v3, v9, v10
	v_fmaak_f32 v8, v7, v8, 0x3f2aaada
	v_sub_f32_e32 v5, v3, v9
	v_ldexp_f32 v9, v6, 1
	v_mul_f32_e32 v6, v6, v7
	v_mul_f32_e32 v6, v6, v8
	v_add_f32_e32 v7, v9, v6
	v_sub_f32_e32 v8, v7, v9
	v_ldexp_f32 v2, v2, 1
	v_sub_f32_e32 v6, v6, v8
	v_add_f32_e32 v2, v2, v6
	v_add_f32_e32 v6, v7, v2
	v_sub_f32_e32 v7, v6, v7
	v_sub_f32_e32 v2, v2, v7
	v_add_f32_e32 v7, v3, v6
	v_sub_f32_e32 v8, v7, v3
	v_sub_f32_e32 v9, v7, v8
	v_sub_f32_e32 v5, v10, v5
	v_sub_f32_e32 v3, v3, v9
	v_sub_f32_e32 v6, v6, v8
	v_add_f32_e32 v3, v6, v3
	v_add_f32_e32 v6, v5, v2
	v_sub_f32_e32 v8, v6, v5
	v_sub_f32_e32 v9, v6, v8
	v_sub_f32_e32 v5, v5, v9
	v_sub_f32_e32 v2, v2, v8
	v_add_f32_e32 v3, v6, v3
	v_add_f32_e32 v2, v2, v5
	v_add_f32_e32 v5, v7, v3
	v_sub_f32_e32 v6, v5, v7
	v_sub_f32_e32 v3, v3, v6
	v_add_f32_e32 v2, v2, v3
	s_mov_b32 s2, 0x7f800000
	v_add_f32_e32 v2, v5, v2
	v_cmp_neq_f32_e32 vcc, s2, v4
	s_mov_b32 s2, 0x33800000
	v_add_u32_e32 v3, -1, v201
	v_cndmask_b32_e32 v2, v202, v2, vcc
	v_cmp_ngt_f32_e32 vcc, -1.0, v4
	s_nop 1
	v_cndmask_b32_e32 v2, v203, v2, vcc
	v_cmp_neq_f32_e32 vcc, -1.0, v4
	s_nop 1
	v_cndmask_b32_e32 v2, v204, v2, vcc
	v_cmp_lt_f32_e64 vcc, |v4|, s2
	s_lshl_b32 s2, s39, 2
	s_ashr_i32 s3, s2, 31
	v_cndmask_b32_e32 v2, v2, v4, vcc
	v_sub_f32_e32 v0, v0, v2
	v_mov_b32_e32 v4, v0
	s_nop 1
	v_add_f32_dpp v4, v0, v4 row_shr:1 row_mask:0xf bank_mask:0xf
	v_add_f32_dpp v4, v0, v4 row_shr:2 row_mask:0xf bank_mask:0xf
	v_add_f32_dpp v4, v0, v4 row_shr:3 row_mask:0xf bank_mask:0xf
	s_nop 1
	v_add_f32_dpp v4, v4, v4 row_shr:4 row_mask:0xf bank_mask:0xe
	s_nop 1
	v_add_f32_dpp v4, v4, v4 row_shr:8 row_mask:0xf bank_mask:0xc
	s_nop 1
	v_add_f32_dpp v4, v4, v4 row_bcast:15 row_mask:0xa bank_mask:0xf
	s_nop 1
	v_add_f32_dpp v4, v4, v4 row_bcast:31 row_mask:0xc bank_mask:0xf
	v_mov_b32_e32 v0, v4
	v_sub_f32_e32 v1, v1, v0
	v_mov_b32_e32 v3, v1
	s_nop 1
	v_max_f32_dpp v3, v1, v3 row_shr:1 row_mask:0xf bank_mask:0xf
	v_max_f32_dpp v3, v1, v3 row_shr:2 row_mask:0xf bank_mask:0xf
	v_max_f32_dpp v3, v1, v3 row_shr:3 row_mask:0xf bank_mask:0xf
	s_nop 1
	v_max_f32_dpp v3, v3, v3 row_shr:4 row_mask:0xf bank_mask:0xe
	s_nop 1
	v_max_f32_dpp v3, v3, v3 row_shr:8 row_mask:0xf bank_mask:0xc
	s_nop 1
	v_max_f32_dpp v3, v3, v3 row_bcast:15 row_mask:0xa bank_mask:0xf
	s_nop 1
	v_max_f32_dpp v3, v3, v3 row_bcast:31 row_mask:0xc bank_mask:0xf
	v_mov_b32_e32 v2, v3
	v_max_f32_e32 v2, v2, v2
	s_waitcnt vmcnt(0)
	v_mov_b32_e32 v3, v42
	v_max_f32_e32 v4, v3, v3
	v_max_f32_e32 v2, v4, v2
	v_lshl_add_u32 v4, v22, 2, 0
	v_add_u32_e32 v4, 0x19200, v4
	ds_write2st64_b32 v4, v1, v2 offset1:1
	v_sub_f32_e32 v1, v3, v2
	v_add_f32_e32 v0, v0, v2
	v_mul_f32_e32 v1, 0x3fb8aa3b, v1
	v_mul_f32_e32 v0, 0xbfb8aa3b, v0
	v_exp_f32_e32 v1, v1
	v_exp_f32_e32 v0, v0
	ds_write2st64_b32 v4, v1, v0 offset0:2 offset1:3
